# attention: next-tile DMA issue block moved behind the first K-fragment LDS reads (covers their latency)
# speedup vs baseline: 1.0100x; 1.0078x over previous
.Latt_diff_p0:
.LBB0_107:
.LBB0_116:
	ds_read_b128 v[112:115], v242 offset:0
	ds_read_b128 v[116:119], v242 offset:4608
	ds_read_b128 v[120:123], v242 offset:32
	ds_read_b128 v[124:127], v242 offset:4640
	s_add_i32 s30, s52, 2
	s_cmp_ge_u32 s30, s21
	s_cselect_b64 s[46:47], -1, 0
	s_cbranch_scc1 .Latt_diff_dmaend
	s_cmp_lt_u32 s52, 2
	s_cselect_b32 s48, s45, s43
	s_mul_i32 s55, s50, 0x2400
	s_add_i32 s56, s55, s41
	s_mov_b32 m0, s56
	v_lshl_add_u32 v244, s48, 12, v153
	global_load_lds_dwordx4 v244, s[18:19]
	s_ashr_i32 s49, s48, 31
	s_lshl_b64 s[30:31], s[48:49], 1
	s_add_i32 s55, s55, s56
	s_add_i32 m0, s55, 0x6c00
	s_add_u32 s30, s39, s30
	s_addc_u32 s31, s42, s31
	global_load_lds_dwordx4 v150, s[30:31]
	s_add_i32 m0, s55, 0x8c00
	s_and_b64 vcc, exec, s[14:15]
	global_load_lds_dwordx4 v148, s[30:31]
	s_cbranch_vccz .Latt_diff_dmax

.Latt_mla_p0:
.LBB0_178:
.LBB0_191:
	ds_read_b128 v[112:115], v209 offset:0
	ds_read_b128 v[116:119], v209 offset:12800
	ds_read_b128 v[120:123], v209 offset:32
	ds_read_b128 v[124:127], v209 offset:12832
	ds_read_b128 v[250:253], v209 offset:64
	s_add_i32 s30, s55, 2
	s_cmp_ge_u32 s30, s20
	s_cselect_b64 s[60:61], -1, 0
	s_cbranch_scc1 .Latt_mla_dmaend
	s_cmp_lt_u32 s55, 2
	s_cselect_b32 s62, s51, s49
	s_mul_i32 s57, s52, 0x6400
	s_add_i32 s57, s57, s42
	s_mov_b32 m0, s57
	v_mad_u32_u24 v217, s62, v237, v222
	global_load_lds_dwordx4 v217, s[2:3]
	s_add_i32 m0, s57, 0x2000
	v_mad_u32_u24 v217, s62, v239, v224
	global_load_lds_dwordx4 v217, s[2:3]
	s_add_i32 m0, s57, 0x4000
	v_mad_u32_u24 v217, s62, v241, v226
	global_load_lds_dwordx4 v217, s[2:3]
	s_ashr_i32 s63, s62, 31
	s_lshl_b64 s[30:31], s[62:63], 1
	s_mul_i32 s63, s52, 0x4800
	s_add_i32 s63, s63, s42
	s_add_i32 m0, s63, 0x12c00
	s_add_u32 s30, s21, s30
	s_addc_u32 s31, s43, s31
	global_load_lds_dwordx4 v202, s[30:31]
	s_add_i32 m0, s63, 0x14c00
	s_and_b64 vcc, exec, s[18:19]
	global_load_lds_dwordx4 v200, s[30:31]
	s_cbranch_vccz .Latt_mla_dmax
